# FFN hidden buffer H in 1KiB-blocked layout (16 rows x 32 cols contiguous): GU stores and DOWN A-tile LDS-DMA loads each cover one contiguous KiB
# baseline (speedup 1.0000x reference)
; template <class Epi>
; DI void gemm_phase(LAS unsigned char* lds, const int tid, const Gemm g, const StaticOrder& S, const Epi& E) {
;     const int wid = __builtin_amdgcn_readfirstlane(tid >> 6), lane = tid & 63, wr = wid >> 2, wc = wid & 3, fr = lane & 15, fq = lane >> 4;
;     const int K = g.K, nt = K / BK, lda = g.lda;
;     unsigned voffA[2], voffB[2];
; #pragma unroll
;     for (int i = 0; i < 2; ++i) { int R, C; stage_rc(tid * 16 + i * 8192, R, C); const int Rb = (R & ~31) + perm32(R & 31);
;         voffA[i] = (unsigned)(R * lda + C) * 2u; voffB[i] = (unsigned)(Rb * K + C) * 2u; }
;     const size_t kstep = (size_t)(BK * 2);
;     const size_t hstepA = (size_t)HALF * lda * 2, hstepB = (size_t)HALF * K * 2;
;     const size_t tstepA = 2 * hstepA, tstepB = 2 * hstepB;
;     const unsigned ldsw = (unsigned)wid * 1024u;
;     const int aoff = lds_byte(wr * 64 + fr, fq * 8), boff = lds_byte(wc * 32 + fr, fq * 8);
.LBB0_436:
	v_readlane_b32 s4, v253, 10
	v_readlane_b32 s5, v253, 11
	s_andn2_b64 vcc, exec, s[4:5]
	v_readfirstlane_b32 s4, v14
	s_cbranch_vccnz .LBB0_656
	v_lshlrev_b32_e32 v0, 4, v14
	v_add_u32_e32 v2, 0x2000, v0
	v_ashrrev_i32_e32 v3, 31, v2
	v_lshrrev_b32_e32 v3, 22, v3
	v_add_u32_e32 v3, v2, v3
	v_ashrrev_i32_e32 v3, 10, v3
	v_mul_i32_i24_e32 v4, 0x400, v3
	v_sub_u32_e32 v2, v2, v4
	v_lshrrev_b32_e32 v4, 4, v2
	v_bitop3_b32 v2, v4, v2, 32 bitop3:0x6c
	v_ashrrev_i32_e32 v4, 31, v2
	v_lshrrev_b32_e32 v4, 26, v4
	v_add_u32_e32 v4, v2, v4
	s_waitcnt lgkmcnt(0)
	v_lshlrev_b32_e32 v6, 3, v3
	v_ashrrev_i32_e32 v5, 6, v4
	v_and_b32_e32 v6, -16, v6
	v_lshlrev_b32_e32 v3, 5, v3
	v_add_u32_e32 v6, v5, v6
	v_and_b32_e32 v15, 32, v3
	v_and_b32_e32 v3, 0xc0, v4
	v_and_b32_e32 v5, 3, v5
	s_mov_b32 s9, 0x7fffffe0
	v_lshrrev_b32_e32 v7, 2, v6
	v_lshlrev_b32_e32 v8, 1, v6
	v_sub_u32_e32 v2, v2, v3
	v_and_or_b32 v5, v6, s9, v5
	v_and_b32_e32 v7, 4, v7
	v_and_b32_e32 v8, 24, v8
	v_ashrrev_i16_sdwa v2, v244, sext(v2) dst_sel:DWORD dst_unused:UNUSED_PAD src0_sel:DWORD src1_sel:BYTE_0
	v_or3_b32 v5, v5, v7, v8
	v_bfe_i32 v16, v2, 0, 16
	v_mul_lo_u32 v5, s6, v5
	v_add_u32_e32 v2, v15, v16
	v_mul_lo_u32 v17, s8, v6
	v_add_lshl_u32 v208, v5, v2, 1
	v_add_lshl_u32 v210, v17, v2, 1
	v_bfe_i32 v2, v14, 27, 1
	v_lshrrev_b32_e32 v2, 22, v2
	v_add_u32_e32 v2, v0, v2
	v_and_b32_e32 v2, 0xfffffc00, v2
	v_sub_u32_e32 v0, v0, v2
	v_lshrrev_b32_e32 v2, 4, v0
	v_ashrrev_i32_e32 v4, 31, v14
	v_bitop3_b32 v0, v2, v0, 32 bitop3:0x6c
	v_lshrrev_b32_e32 v4, 26, v4
	v_ashrrev_i32_e32 v2, 31, v0
	v_add_u32_e32 v4, v14, v4
	v_lshrrev_b32_e32 v2, 26, v2
	v_ashrrev_i32_e32 v4, 6, v4
	v_add_u32_e32 v2, v0, v2
	v_lshlrev_b32_e32 v5, 3, v4
	v_ashrrev_i32_e32 v3, 6, v2
	v_and_b32_e32 v5, -16, v5
	s_lshl_b32 s88, s8, 8
	s_mov_b32 s89, s47
	v_add_u32_e32 v5, v3, v5
	v_and_b32_e32 v3, 3, v3
	s_lshl_b64 s[90:91], s[88:89], 1
	v_and_or_b32 v3, v5, s9, v3
	v_readlane_b32 s9, v253, 24
	v_readlane_b32 s11, v253, 23
	v_mul_lo_u32 v20, s8, v5
	s_mul_i32 s9, s90, s9
	s_mul_hi_u32 s10, s90, s11
	s_bfe_u32 s8, s8, 0x10017
	s_add_i32 s9, s10, s9
	s_mul_i32 s8, s8, s11
	s_mul_i32 s12, s90, s11
	v_readlane_b32 s10, v253, 25
	s_lshl_b32 s15, s6, 9
	v_and_b32_e32 v2, 0xc0, v2
	v_readlane_b32 s11, v253, 26
	s_ashr_i32 s7, s4, 6
	v_lshrrev_b32_e32 v6, 2, v5
	v_lshlrev_b32_e32 v7, 1, v5
	v_sub_u32_e32 v0, v0, v2
	s_add_i32 s13, s9, s8
	s_mul_i32 s8, s15, s11
	s_mul_hi_u32 s9, s15, s10
	s_ashr_i32 s5, s4, 8
	s_lshl_b32 s14, s6, 8
	s_lshl_b32 s30, s7, 10
	v_and_b32_e32 v6, 4, v6
	v_and_b32_e32 v7, 24, v7
	v_lshlrev_b32_e32 v4, 5, v4
	v_ashrrev_i16_sdwa v0, v244, sext(v0) dst_sel:DWORD dst_unused:UNUSED_PAD src0_sel:DWORD src1_sel:BYTE_0
	s_add_i32 s9, s9, s8
	s_mul_i32 s8, s15, s10
	v_or3_b32 v3, v3, v6, v7
	s_waitcnt lgkmcnt(0)
	v_and_b32_e32 v18, 32, v4
	v_bfe_i32 v19, v0, 0, 16
	s_add_u32 s10, s62, s8
	v_mul_lo_u32 v3, s6, v3
	v_add_u32_e32 v2, v18, v19
	s_addc_u32 s11, s63, s9
	s_add_i32 s31, s30, 0
	v_add_lshl_u32 v0, v3, v2, 1
	s_add_i32 m0, s31, 0x10000
	v_mov_b32_e32 v209, v1
	global_load_lds_dwordx4 v0, s[10:11]
	s_add_i32 m0, s31, 0x12000
	s_add_u32 s8, s10, s14
	global_load_lds_dwordx4 v208, s[10:11]
	s_addc_u32 s9, s11, 0
	s_add_i32 m0, s31, 0x14000
	v_add_lshl_u32 v212, v20, v2, 1
	s_cmp_lg_u32 s6, 0xb00
	s_movk_i32 s100, 0x800
	s_cselect_b32 s100, 0x80, s100
	s_mov_b32 s101, 0
	s_cbranch_scc1 .Lrs_lin1
	v_lshrrev_b32_e32 v190, 7, v14
	v_mul_u32_u24_e32 v190, 0x58, v190
	v_bfe_u32 v191, v14, 6, 1
	v_add_u32_e32 v190, v190, v191
	v_lshlrev_b32_e32 v190, 10, v190
	v_bfe_u32 v191, v14, 2, 3
	v_lshl_add_u32 v190, v191, 7, v190
	v_bfe_u32 v191, v14, 5, 1
	v_lshl_add_u32 v190, v191, 6, v190
	v_lshlrev_b32_e32 v191, 1, v191
	v_and_b32_e32 v192, 3, v14
	v_xor_b32_e32 v191, v191, v192
	v_lshl_add_u32 v212, v191, 4, v190
	v_add_u32_e32 v210, 0x58000, v212
; #define PG8_STAGE(bufoff, gbase, voff) do { _Pragma("unroll") for (int _i = 0; _i < 2; ++_i) \
;         __builtin_amdgcn_global_load_lds((const unsigned*)((const char*)(gbase) + (voff)[_i]), (LAS unsigned*)(lds + (bufoff) + ldsw + _i * 8192), 16, 0, 0); } while (0)
; #define PG8_WAIT_V(n) asm volatile("s_waitcnt vmcnt(" #n ")" ::: "memory")
; #define PG8_BAR __builtin_amdgcn_s_barrier()
; template <class Epi>
; DI void gemm_phase(LAS unsigned char* lds, const int tid, const Gemm g, const StaticOrder& S, const Epi& E) {
;     ...
;     PG8_STAGE(PG8_SB(0, 0), cB, voffB); PG8_STAGE(PG8_SB(0, 1), cB + hstepB, voffB); PG8_STAGE(PG8_SA(0, 0), cA, voffA); PG8_STAGE(PG8_SA(0, 1), cA + hstepA, voffA);
;     if (wr == 1) PG8_BAR;
;     PG8_WAIT_V(2); PG8_BAR;
;     PG8_STAGE(PG8_SB(1, 0), cB + kstep, voffB); PG8_STAGE(PG8_SA(1, 0), cA + kstep, voffA); PG8_STAGE(PG8_SB(1, 1), cB + hstepB + kstep, voffB);
;     PG8_WAIT_V(6); PG8_BAR;
.Lrs_lin1:
	global_load_lds_dwordx4 v0, s[8:9]
	s_add_i32 m0, s31, 0x16000
	s_add_u32 s12, s64, s12
	s_addc_u32 s13, s65, s13
	s_add_i32 s38, s31, 0x2000
	v_lshl_add_u64 v[6:7], s[8:9], 0, v[0:1]
	v_lshl_add_u64 v[8:9], s[8:9], 0, v[208:209]
	global_load_lds_dwordx4 v208, s[8:9]
	s_mov_b32 m0, s31
	s_add_u32 s8, s12, s88
	global_load_lds_dwordx4 v212, s[12:13]
	s_mov_b32 m0, s38
	s_addc_u32 s9, s13, 0
	s_add_i32 s45, s31, 0x4000
	global_load_lds_dwordx4 v210, s[12:13]
	s_mov_b32 m0, s45
	s_add_i32 s24, s31, 0x6000
	global_load_lds_dwordx4 v212, s[8:9]
	s_mov_b32 m0, s24
	v_mov_b32_e32 v213, v1
	global_load_lds_dwordx4 v210, s[8:9]
	v_mov_b32_e32 v211, v1
	s_cmp_eq_u32 s5, 1
	v_mov_b64_e32 v[206:207], 0x400
	s_mov_b32 s70, s80
	v_readlane_b32 s33, v253, 0
	v_lshl_add_u64 v[2:3], s[10:11], 0, v[0:1]
	v_lshl_add_u64 v[4:5], s[10:11], 0, v[208:209]
	v_lshl_add_u64 v[10:11], s[12:13], 0, v[212:213]
	v_lshl_add_u64 v[12:13], s[12:13], 0, v[210:211]
	s_cselect_b64 s[48:49], -1, 0
	s_cmp_lg_u32 s5, 1
	s_cbranch_scc1 .LBB0_439
	s_barrier
.LBB0_439:
	s_add_i32 m0, s31, 0x18000
	v_lshl_add_u64 v[2:3], v[2:3], 0, s[54:55]
	s_waitcnt vmcnt(2)
	s_barrier
	global_load_lds_dwordx4 v[2:3], off
	v_lshl_add_u64 v[2:3], v[4:5], 0, s[54:55]
	s_add_i32 m0, s31, 0x1a000
	s_add_i32 s25, s31, 0x8000
	global_load_lds_dwordx4 v[2:3], off
	v_lshl_add_u64 v[2:3], v[10:11], 0, s[100:101]
	s_mov_b32 m0, s25
	s_add_i32 s42, s31, 0xa000
	global_load_lds_dwordx4 v[2:3], off
	v_lshl_add_u64 v[2:3], v[12:13], 0, s[100:101]
	s_mov_b32 m0, s42
	s_and_b32 s43, s7, 3
	global_load_lds_dwordx4 v[2:3], off
	s_add_i32 m0, s31, 0x1c000
	v_lshl_add_u64 v[2:3], v[6:7], 0, s[54:55]
	global_load_lds_dwordx4 v[2:3], off
	v_lshl_add_u64 v[2:3], v[8:9], 0, s[54:55]
	s_add_i32 m0, s31, 0x1e000
	s_lshr_b32 s96, s6, 6
	global_load_lds_dwordx4 v[2:3], off
	v_bfe_u32 v2, v14, 4, 2
	v_and_b32_e32 v3, 15, v14
	v_lshlrev_b32_e32 v5, 4, v2
	v_lshl_or_b32 v250, s5, 6, v3
	v_lshl_or_b32 v3, v3, 6, v5
	v_lshlrev_b32_e32 v5, 2, v14
	s_lshl_b32 s5, s5, 13
	v_and_b32_e32 v5, 32, v5
	v_bitop3_b32 v6, v3, s5, v5 bitop3:0xde
	s_lshl_b32 s5, s43, 12
	s_add_i32 s97, s96, -2
	s_cmpk_lt_u32 s4, 0x100
	s_cselect_b64 s[56:57], -1, 0
	s_ashr_i32 s93, s39, 31
	v_lshlrev_b32_e32 v4, 3, v2
	v_bitop3_b32 v251, s5, v3, v5 bitop3:0xf6
	v_cmp_eq_u32_e64 s[4:5], 0, v2
	s_cmp_lg_u64 s[34:35], 0
	v_add_u32_e32 v2, v20, v18
	s_cselect_b64 s[58:59], -1, 0
	s_cmp_lg_u64 s[40:41], 0
	v_readlane_b32 s6, v255, 5
	v_add_lshl_u32 v2, v2, v19, 1
	v_mov_b32_e32 v3, v1
	s_waitcnt vmcnt(6)
	s_cselect_b64 s[78:79], -1, 0
	s_cmp_lg_u64 s[72:73], 0
	v_readlane_b32 s7, v255, 6
	v_lshl_add_u64 v[214:215], s[88:89], 0, v[2:3]
	v_add_u32_e32 v2, v17, v15
	s_cselect_b64 s[60:61], -1, 0
	s_cmp_lg_u64 s[6:7], 0
	v_add_lshl_u32 v2, v2, v16, 1
	v_lshl_or_b32 v252, s43, 5, v4
	s_mov_b32 s92, 0
	s_mov_b32 s67, s66
	s_mov_b32 s84, s66
	s_mov_b32 s85, s66
	s_cselect_b64 s[52:53], -1, 0
	v_lshl_add_u64 v[216:217], s[88:89], 0, v[2:3]
	s_cmp_eq_u32 s100, 0x800
	s_cbranch_scc0 .Lrs_lin2
	v_add_u32_e32 v214, s88, v212
	v_add_u32_e32 v216, s88, v210
	v_mov_b32_e32 v215, v1
	v_mov_b32_e32 v217, v1
.Lrs_lin2:
	v_add_u32_e32 v243, 0, v6
	v_readlane_b32 s95, v253, 17
	v_readlane_b32 s46, v253, 23
	s_barrier
	s_branch .LBB0_442

; #define PG8_STAGE(bufoff, gbase, voff) do { _Pragma("unroll") for (int _i = 0; _i < 2; ++_i) \
;         __builtin_amdgcn_global_load_lds((const unsigned*)((const char*)(gbase) + (voff)[_i]), (LAS unsigned*)(lds + (bufoff) + ldsw + _i * 8192), 16, 0, 0); } while (0)
; #define PG8_LDA(dst, b, h) do { _Pragma("unroll") for (int m = 0; m < 4; ++m) _Pragma("unroll") for (int k = 0; k < 2; ++k) dst[m][k] = *(const LAS bf16x8*)(lds + PG8_SA(b, h) + aoff + m * 2048 + k * 1024); } while (0)
; #define PG8_LDB(dst, b, h) do { _Pragma("unroll") for (int n = 0; n < 2; ++n) _Pragma("unroll") for (int k = 0; k < 2; ++k) dst[n][k] = *(const LAS bf16x8*)(lds + PG8_SB(b, h) + boff + n * 2048 + k * 1024); } while (0)
; #define PG8_MMA(ai, bj, At, Bt) do { __builtin_amdgcn_s_setprio(1); _Pragma("unroll") for (int m = 0; m < 4; ++m) _Pragma("unroll") for (int n = 0; n < 2; ++n) _Pragma("unroll") for (int k = 0; k < 2; ++k) \
;         acc[ai][bj][m][n] = __builtin_amdgcn_mfma_f32_16x16x32_bf16(Bt[n][k], At[m][k], acc[ai][bj][m][n], 0, 0, 0); __builtin_amdgcn_s_setprio(0); } while (0)
; #define PG8_WAIT_V(n) asm volatile("s_waitcnt vmcnt(" #n ")" ::: "memory")
; template <class Epi>
; DI void gemm_phase(LAS unsigned char* lds, const int tid, const Gemm g, const StaticOrder& S, const Epi& E) {
;     ...
;         for (int t = 0; t < nt; t += 2) {
;             const bool last = (t == nt - 2);
;             const char* a1 = cA + (size_t)(t + 1) * kstep;
;             const char* a2 = last ? nA : cA + (size_t)(t + 2) * kstep; const char* b2 = last ? nB : cB + (size_t)(t + 2) * kstep;
;             const char* a3 = a2 + kstep; const char* b3 = b2 + kstep;
;             PG8_LDB(B0, 0, 0); PG8_LDB(B1, 0, 1); PG8_SCHED; PG8_LDA(At, 0, 0); PG8_STAGE(PG8_SA(1, 1), a1 + hstepA, voffA);
;             PG8_WAIT_V(8); PG8_WAIT_L(0); PG8_BAR; PG8_MMA(0, 0, At, B0); PG8_MMA(0, 1, At, B1); PG8_BAR; PG8_SCHED;
;             PG8_LDA(At, 0, 1); PG8_STAGE(PG8_SB(0, 0), b2, voffB); PG8_STAGE(PG8_SB(0, 1), b2 + hstepB, voffB); PG8_STAGE(PG8_SA(0, 0), a2, voffA);
;     ...
;         for (int a = 0; a < 2; ++a)
; #pragma unroll
;             for (int b = 0; b < 2; ++b)
; #pragma unroll
;                 for (int m = 0; m < 4; ++m)
; #pragma unroll
;                     for (int n = 0; n < 2; ++n) acc[a][b][m][n] = (f32x4){0.f, 0.f, 0.f, 0.f};
;         cur = nxt; cA = nA; cB = nB; ++ui;
.LBB0_452:
	s_add_u32 s8, s12, s100
	s_addc_u32 s9, s13, 0
	s_add_u32 s12, s10, 0x100
	v_mov_b32_e32 v2, 0
	s_addc_u32 s13, s11, 0
	s_mov_b32 s10, 0
	v_mov_b32_e32 v3, v2
	v_mov_b32_e32 v4, v2
	v_mov_b32_e32 v5, v2
	v_mov_b32_e32 v6, v2
	v_mov_b32_e32 v7, v2
	v_mov_b32_e32 v8, v2
	v_mov_b32_e32 v9, v2
	v_mov_b32_e32 v18, v2
	v_mov_b32_e32 v19, v2
	v_mov_b32_e32 v20, v2
	v_mov_b32_e32 v21, v2
	v_mov_b32_e32 v22, v2
	v_mov_b32_e32 v23, v2
	v_mov_b32_e32 v24, v2
	v_mov_b32_e32 v25, v2
	v_mov_b32_e32 v34, v2
	v_mov_b32_e32 v35, v2
	v_mov_b32_e32 v36, v2
	v_mov_b32_e32 v37, v2
	v_mov_b32_e32 v38, v2
	v_mov_b32_e32 v39, v2
	v_mov_b32_e32 v40, v2
	v_mov_b32_e32 v41, v2
	v_mov_b32_e32 v50, v2
	v_mov_b32_e32 v51, v2
	v_mov_b32_e32 v52, v2
	v_mov_b32_e32 v53, v2
	v_mov_b32_e32 v54, v2
	v_mov_b32_e32 v55, v2
	v_mov_b32_e32 v56, v2
	v_mov_b32_e32 v57, v2
	v_mov_b32_e32 v10, v2
	v_mov_b32_e32 v11, v2
	v_mov_b32_e32 v12, v2
	v_mov_b32_e32 v13, v2
	v_mov_b32_e32 v14, v2
	v_mov_b32_e32 v15, v2
	v_mov_b32_e32 v16, v2
	v_mov_b32_e32 v17, v2
	v_mov_b32_e32 v26, v2
	v_mov_b32_e32 v27, v2
	v_mov_b32_e32 v28, v2
	v_mov_b32_e32 v29, v2
	v_mov_b32_e32 v30, v2
	v_mov_b32_e32 v31, v2
	v_mov_b32_e32 v32, v2
	v_mov_b32_e32 v33, v2
	v_mov_b32_e32 v42, v2
	v_mov_b32_e32 v43, v2
	v_mov_b32_e32 v44, v2
	v_mov_b32_e32 v45, v2
	v_mov_b32_e32 v46, v2
	v_mov_b32_e32 v47, v2
	v_mov_b32_e32 v48, v2
	v_mov_b32_e32 v49, v2
	v_mov_b32_e32 v58, v2
	v_mov_b32_e32 v59, v2
	v_mov_b32_e32 v60, v2
	v_mov_b32_e32 v61, v2
	v_mov_b32_e32 v62, v2
	v_mov_b32_e32 v63, v2
	v_mov_b32_e32 v64, v2
	v_mov_b32_e32 v65, v2
	v_mov_b32_e32 v66, v2
	v_mov_b32_e32 v67, v2
	v_mov_b32_e32 v68, v2
	v_mov_b32_e32 v69, v2
	v_mov_b32_e32 v70, v2
	v_mov_b32_e32 v71, v2
	v_mov_b32_e32 v72, v2
	v_mov_b32_e32 v73, v2
	v_mov_b32_e32 v82, v2
	v_mov_b32_e32 v83, v2
	v_mov_b32_e32 v84, v2
	v_mov_b32_e32 v85, v2
	v_mov_b32_e32 v86, v2
	v_mov_b32_e32 v87, v2
	v_mov_b32_e32 v88, v2
	v_mov_b32_e32 v89, v2
	v_mov_b32_e32 v98, v2
	v_mov_b32_e32 v99, v2
	v_mov_b32_e32 v100, v2
	v_mov_b32_e32 v101, v2
	v_mov_b32_e32 v102, v2
	v_mov_b32_e32 v103, v2
	v_mov_b32_e32 v104, v2
	v_mov_b32_e32 v105, v2
	v_mov_b32_e32 v114, v2
	v_mov_b32_e32 v115, v2
	v_mov_b32_e32 v116, v2
	v_mov_b32_e32 v117, v2
	v_mov_b32_e32 v118, v2
	v_mov_b32_e32 v119, v2
	v_mov_b32_e32 v120, v2
	v_mov_b32_e32 v121, v2
	v_mov_b32_e32 v74, v2
	v_mov_b32_e32 v75, v2
	v_mov_b32_e32 v76, v2
	v_mov_b32_e32 v77, v2
	v_mov_b32_e32 v78, v2
	v_mov_b32_e32 v79, v2
	v_mov_b32_e32 v80, v2
	v_mov_b32_e32 v81, v2
	v_mov_b32_e32 v90, v2
	v_mov_b32_e32 v91, v2
	v_mov_b32_e32 v92, v2
	v_mov_b32_e32 v93, v2
	v_mov_b32_e32 v94, v2
	v_mov_b32_e32 v95, v2
	v_mov_b32_e32 v96, v2
	v_mov_b32_e32 v97, v2
	v_mov_b32_e32 v106, v2
	v_mov_b32_e32 v107, v2
	v_mov_b32_e32 v108, v2
	v_mov_b32_e32 v109, v2
	v_mov_b32_e32 v110, v2
	v_mov_b32_e32 v111, v2
	v_mov_b32_e32 v112, v2
	v_mov_b32_e32 v113, v2
	v_mov_b32_e32 v122, v2
	v_mov_b32_e32 v123, v2
	v_mov_b32_e32 v124, v2
	v_mov_b32_e32 v125, v2
	v_mov_b32_e32 v126, v2
	v_mov_b32_e32 v127, v2
	v_mov_b32_e32 v128, v2
	v_mov_b32_e32 v129, v2
.LBB0_453:
	s_add_i32 s82, s10, 2
	s_add_u32 s26, s8, s100
	s_addc_u32 s11, s9, 0
	s_add_i32 s27, 0, 0x10000
	s_cmp_eq_u32 s97, s10
	s_cselect_b32 s11, s37, s11
	s_cselect_b32 s10, s36, s26
	s_cselect_b32 vcc_hi, s81, s13
	s_cselect_b32 vcc_lo, s80, s12
	s_add_i32 s26, 0, 0x14000
	v_add_u32_e32 v142, s27, v251
	v_add_u32_e32 v158, s26, v251
	ds_read_b128 v[130:133], v142
	ds_read_b128 v[134:137], v142 offset:1024
	ds_read_b128 v[138:141], v142 offset:2048
	ds_read_b128 v[142:145], v142 offset:3072
	ds_read_b128 v[146:149], v158
	ds_read_b128 v[150:153], v158 offset:1024
	ds_read_b128 v[154:157], v158 offset:2048
	ds_read_b128 v[158:161], v158 offset:3072
	v_lshl_add_u64 v[194:195], s[8:9], 0, v[214:215]
	s_add_i32 m0, s31, 0xc000
	ds_read_b128 v[162:165], v243
	ds_read_b128 v[166:169], v243 offset:1024
	ds_read_b128 v[170:173], v243 offset:2048
	ds_read_b128 v[174:177], v243 offset:3072
	ds_read_b128 v[178:181], v243 offset:4096
	ds_read_b128 v[182:185], v243 offset:5120
	ds_read_b128 v[186:189], v243 offset:6144
	ds_read_b128 v[190:193], v243 offset:7168
	global_load_lds_dwordx4 v[194:195], off
	v_lshl_add_u64 v[194:195], s[8:9], 0, v[216:217]
	s_add_i32 m0, s31, 0xe000
	s_nop 0
	global_load_lds_dwordx4 v[194:195], off
	s_waitcnt vmcnt(8)
	s_waitcnt lgkmcnt(0)
	s_barrier
	s_setprio 1
	s_waitcnt lgkmcnt(0)
	v_mfma_f32_16x16x32_bf16 v[126:129], v[130:133], v[162:165], v[126:129]
	v_mfma_f32_16x16x32_bf16 v[122:125], v[138:141], v[162:165], v[122:125]
	v_mfma_f32_16x16x32_bf16 v[110:113], v[130:133], v[170:173], v[110:113]
	v_mfma_f32_16x16x32_bf16 v[106:109], v[138:141], v[170:173], v[106:109]
	v_mfma_f32_16x16x32_bf16 v[94:97], v[130:133], v[178:181], v[94:97]
	v_mfma_f32_16x16x32_bf16 v[90:93], v[138:141], v[178:181], v[90:93]
	v_mfma_f32_16x16x32_bf16 v[78:81], v[130:133], v[186:189], v[78:81]
	v_mfma_f32_16x16x32_bf16 v[74:77], v[138:141], v[186:189], v[74:77]
	v_mfma_f32_16x16x32_bf16 v[126:129], v[134:137], v[166:169], v[126:129]
	v_mfma_f32_16x16x32_bf16 v[122:125], v[142:145], v[166:169], v[122:125]
	v_mfma_f32_16x16x32_bf16 v[110:113], v[134:137], v[174:177], v[110:113]
	v_mfma_f32_16x16x32_bf16 v[106:109], v[142:145], v[174:177], v[106:109]
	v_mfma_f32_16x16x32_bf16 v[94:97], v[134:137], v[182:185], v[94:97]
	v_mfma_f32_16x16x32_bf16 v[90:93], v[142:145], v[182:185], v[90:93]
	v_mfma_f32_16x16x32_bf16 v[78:81], v[134:137], v[190:193], v[78:81]
	v_mfma_f32_16x16x32_bf16 v[74:77], v[142:145], v[190:193], v[74:77]
	s_setprio 0
	s_setprio 1
	v_mfma_f32_16x16x32_bf16 v[118:121], v[146:149], v[162:165], v[118:121]
	v_mfma_f32_16x16x32_bf16 v[114:117], v[154:157], v[162:165], v[114:117]
	v_mfma_f32_16x16x32_bf16 v[102:105], v[146:149], v[170:173], v[102:105]
	v_mfma_f32_16x16x32_bf16 v[98:101], v[154:157], v[170:173], v[98:101]
	v_mfma_f32_16x16x32_bf16 v[86:89], v[146:149], v[178:181], v[86:89]
	v_mfma_f32_16x16x32_bf16 v[82:85], v[154:157], v[178:181], v[82:85]
	v_mfma_f32_16x16x32_bf16 v[70:73], v[146:149], v[186:189], v[70:73]
	v_mfma_f32_16x16x32_bf16 v[66:69], v[154:157], v[186:189], v[66:69]
	v_mfma_f32_16x16x32_bf16 v[118:121], v[150:153], v[166:169], v[118:121]
	v_mfma_f32_16x16x32_bf16 v[114:117], v[158:161], v[166:169], v[114:117]
	v_mfma_f32_16x16x32_bf16 v[102:105], v[150:153], v[174:177], v[102:105]
	v_mfma_f32_16x16x32_bf16 v[98:101], v[158:161], v[174:177], v[98:101]
	v_mfma_f32_16x16x32_bf16 v[86:89], v[150:153], v[182:185], v[86:89]
	v_mfma_f32_16x16x32_bf16 v[82:85], v[158:161], v[182:185], v[82:85]
	v_mfma_f32_16x16x32_bf16 v[70:73], v[150:153], v[190:193], v[70:73]
	v_mfma_f32_16x16x32_bf16 v[66:69], v[158:161], v[190:193], v[66:69]
	s_setprio 0
	s_barrier
; #define PG8_STAGE(bufoff, gbase, voff) do { _Pragma("unroll") for (int _i = 0; _i < 2; ++_i) \
;         __builtin_amdgcn_global_load_lds((const unsigned*)((const char*)(gbase) + (voff)[_i]), (LAS unsigned*)(lds + (bufoff) + ldsw + _i * 8192), 16, 0, 0); } while (0)
; #define PG8_LDA(dst, b, h) do { _Pragma("unroll") for (int m = 0; m < 4; ++m) _Pragma("unroll") for (int k = 0; k < 2; ++k) dst[m][k] = *(const LAS bf16x8*)(lds + PG8_SA(b, h) + aoff + m * 2048 + k * 1024); } while (0)
; #define PG8_LDB(dst, b, h) do { _Pragma("unroll") for (int n = 0; n < 2; ++n) _Pragma("unroll") for (int k = 0; k < 2; ++k) dst[n][k] = *(const LAS bf16x8*)(lds + PG8_SB(b, h) + boff + n * 2048 + k * 1024); } while (0)
; #define PG8_MMA(ai, bj, At, Bt) do { __builtin_amdgcn_s_setprio(1); _Pragma("unroll") for (int m = 0; m < 4; ++m) _Pragma("unroll") for (int n = 0; n < 2; ++n) _Pragma("unroll") for (int k = 0; k < 2; ++k) \
;         acc[ai][bj][m][n] = __builtin_amdgcn_mfma_f32_16x16x32_bf16(Bt[n][k], At[m][k], acc[ai][bj][m][n], 0, 0, 0); __builtin_amdgcn_s_setprio(0); } while (0)
; #define PG8_WAIT_V(n) asm volatile("s_waitcnt vmcnt(" #n ")" ::: "memory")
; #define PG8_WAIT_L(n) asm volatile("s_waitcnt lgkmcnt(" #n ")" ::: "memory")
; #define PG8_BAR __builtin_amdgcn_s_barrier()
; #define PG8_SCHED __builtin_amdgcn_sched_barrier(0)
; template <class Epi>
; DI void gemm_phase(LAS unsigned char* lds, const int tid, const Gemm g, const StaticOrder& S, const Epi& E) {
;     ...
;             PG8_LDA(At, 0, 1); PG8_STAGE(PG8_SB(0, 0), b2, voffB); PG8_STAGE(PG8_SB(0, 1), b2 + hstepB, voffB); PG8_STAGE(PG8_SA(0, 0), a2, voffA);
;             PG8_WAIT_V(8); PG8_WAIT_L(0); PG8_BAR; PG8_MMA(1, 0, At, B0); PG8_MMA(1, 1, At, B1); PG8_BAR; PG8_SCHED;
;             PG8_LDB(B0, 1, 0); PG8_LDB(B1, 1, 1); PG8_SCHED; PG8_LDA(At, 1, 0); PG8_STAGE(PG8_SA(0, 1), a2 + hstepA, voffA);
;             PG8_WAIT_V(8); PG8_WAIT_L(0); PG8_BAR; PG8_MMA(0, 0, At, B0); PG8_MMA(0, 1, At, B1); PG8_BAR; PG8_SCHED;
	s_add_i32 s27, s27, s30
	v_lshl_add_u64 v[194:195], vcc, 0, v[0:1]
	s_mov_b32 m0, s27
	ds_read_b128 v[162:165], v243 offset:16384
	ds_read_b128 v[166:169], v243 offset:17408
	ds_read_b128 v[170:173], v243 offset:18432
	ds_read_b128 v[174:177], v243 offset:19456
	ds_read_b128 v[178:181], v243 offset:20480
	ds_read_b128 v[182:185], v243 offset:21504
	ds_read_b128 v[186:189], v243 offset:22528
	ds_read_b128 v[190:193], v243 offset:23552
	global_load_lds_dwordx4 v[194:195], off
	s_add_i32 m0, s27, 0x2000
	v_lshl_add_u64 v[196:197], vcc, 0, v[208:209]
	s_add_u32 vcc_lo, vcc_lo, s14
	s_addc_u32 vcc_hi, vcc_hi, 0
	s_add_i32 s26, s26, s30
	global_load_lds_dwordx4 v[196:197], off
	v_lshl_add_u64 v[198:199], vcc, 0, v[0:1]
	s_mov_b32 m0, s26
	v_lshl_add_u64 v[200:201], vcc, 0, v[208:209]
	global_load_lds_dwordx4 v[198:199], off
	s_add_i32 m0, s26, 0x2000
	v_lshl_add_u64 v[202:203], s[10:11], 0, v[212:213]
	global_load_lds_dwordx4 v[200:201], off
	s_mov_b32 m0, s31
	v_lshl_add_u64 v[204:205], s[10:11], 0, v[210:211]
	global_load_lds_dwordx4 v[202:203], off
	s_mov_b32 m0, s38
	s_nop 0
	global_load_lds_dwordx4 v[204:205], off
	s_waitcnt vmcnt(8)
	s_waitcnt lgkmcnt(0)
	s_barrier
	s_setprio 1
	s_waitcnt lgkmcnt(0)
	v_mfma_f32_16x16x32_bf16 v[62:65], v[130:133], v[162:165], v[62:65]
	v_mfma_f32_16x16x32_bf16 v[58:61], v[138:141], v[162:165], v[58:61]
	v_mfma_f32_16x16x32_bf16 v[46:49], v[130:133], v[170:173], v[46:49]
	v_mfma_f32_16x16x32_bf16 v[42:45], v[138:141], v[170:173], v[42:45]
	v_mfma_f32_16x16x32_bf16 v[30:33], v[130:133], v[178:181], v[30:33]
	v_mfma_f32_16x16x32_bf16 v[26:29], v[138:141], v[178:181], v[26:29]
	v_mfma_f32_16x16x32_bf16 v[14:17], v[130:133], v[186:189], v[14:17]
	v_mfma_f32_16x16x32_bf16 v[10:13], v[138:141], v[186:189], v[10:13]
	v_mfma_f32_16x16x32_bf16 v[62:65], v[134:137], v[166:169], v[62:65]
	v_mfma_f32_16x16x32_bf16 v[58:61], v[142:145], v[166:169], v[58:61]
	v_mfma_f32_16x16x32_bf16 v[46:49], v[134:137], v[174:177], v[46:49]
	v_mfma_f32_16x16x32_bf16 v[42:45], v[142:145], v[174:177], v[42:45]
	v_mfma_f32_16x16x32_bf16 v[30:33], v[134:137], v[182:185], v[30:33]
	v_mfma_f32_16x16x32_bf16 v[26:29], v[142:145], v[182:185], v[26:29]
	v_mfma_f32_16x16x32_bf16 v[14:17], v[134:137], v[190:193], v[14:17]
	v_mfma_f32_16x16x32_bf16 v[10:13], v[142:145], v[190:193], v[10:13]
	s_setprio 0
	s_setprio 1
	v_mfma_f32_16x16x32_bf16 v[54:57], v[146:149], v[162:165], v[54:57]
	v_mfma_f32_16x16x32_bf16 v[50:53], v[154:157], v[162:165], v[50:53]
	v_mfma_f32_16x16x32_bf16 v[38:41], v[146:149], v[170:173], v[38:41]
	v_mfma_f32_16x16x32_bf16 v[34:37], v[154:157], v[170:173], v[34:37]
	v_mfma_f32_16x16x32_bf16 v[22:25], v[146:149], v[178:181], v[22:25]
	v_mfma_f32_16x16x32_bf16 v[18:21], v[154:157], v[178:181], v[18:21]
	v_mfma_f32_16x16x32_bf16 v[6:9], v[146:149], v[186:189], v[6:9]
	v_mfma_f32_16x16x32_bf16 v[2:5], v[154:157], v[186:189], v[2:5]
	v_mfma_f32_16x16x32_bf16 v[54:57], v[150:153], v[166:169], v[54:57]
	v_mfma_f32_16x16x32_bf16 v[50:53], v[158:161], v[166:169], v[50:53]
	v_mfma_f32_16x16x32_bf16 v[38:41], v[150:153], v[174:177], v[38:41]
	v_mfma_f32_16x16x32_bf16 v[34:37], v[158:161], v[174:177], v[34:37]
	v_mfma_f32_16x16x32_bf16 v[22:25], v[150:153], v[182:185], v[22:25]
	v_mfma_f32_16x16x32_bf16 v[18:21], v[158:161], v[182:185], v[18:21]
	v_mfma_f32_16x16x32_bf16 v[6:9], v[150:153], v[190:193], v[6:9]
	v_mfma_f32_16x16x32_bf16 v[2:5], v[158:161], v[190:193], v[2:5]
	s_setprio 0
	s_barrier
	s_add_i32 s26, 0, 0x18000
	s_add_i32 s27, 0, 0x1c000
	v_add_u32_e32 v142, s26, v251
	v_add_u32_e32 v158, s27, v251
	ds_read_b128 v[130:133], v142
	ds_read_b128 v[134:137], v142 offset:1024
	ds_read_b128 v[138:141], v142 offset:2048
	ds_read_b128 v[142:145], v142 offset:3072
	ds_read_b128 v[146:149], v158
	ds_read_b128 v[150:153], v158 offset:1024
	ds_read_b128 v[154:157], v158 offset:2048
	ds_read_b128 v[158:161], v158 offset:3072
	s_add_u32 s10, s10, s88
	s_addc_u32 s11, s11, 0
	s_mov_b32 m0, s45
	v_lshl_add_u64 v[218:219], s[10:11], 0, v[212:213]
	ds_read_b128 v[162:165], v243 offset:32768
	ds_read_b128 v[166:169], v243 offset:33792
	ds_read_b128 v[170:173], v243 offset:34816
	ds_read_b128 v[174:177], v243 offset:35840
	ds_read_b128 v[178:181], v243 offset:36864
	ds_read_b128 v[182:185], v243 offset:37888
	ds_read_b128 v[186:189], v243 offset:38912
	ds_read_b128 v[190:193], v243 offset:39936
	global_load_lds_dwordx4 v[218:219], off
	v_lshl_add_u64 v[218:219], s[10:11], 0, v[210:211]
	s_mov_b32 m0, s24
	s_nop 0
	global_load_lds_dwordx4 v[218:219], off
	s_waitcnt vmcnt(8)
	s_waitcnt lgkmcnt(0)
	s_barrier
; #define PG8_STAGE(bufoff, gbase, voff) do { _Pragma("unroll") for (int _i = 0; _i < 2; ++_i) \
;         __builtin_amdgcn_global_load_lds((const unsigned*)((const char*)(gbase) + (voff)[_i]), (LAS unsigned*)(lds + (bufoff) + ldsw + _i * 8192), 16, 0, 0); } while (0)
; #define PG8_LDA(dst, b, h) do { _Pragma("unroll") for (int m = 0; m < 4; ++m) _Pragma("unroll") for (int k = 0; k < 2; ++k) dst[m][k] = *(const LAS bf16x8*)(lds + PG8_SA(b, h) + aoff + m * 2048 + k * 1024); } while (0)
; #define PG8_LDB(dst, b, h) do { _Pragma("unroll") for (int n = 0; n < 2; ++n) _Pragma("unroll") for (int k = 0; k < 2; ++k) dst[n][k] = *(const LAS bf16x8*)(lds + PG8_SB(b, h) + boff + n * 2048 + k * 1024); } while (0)
; #define PG8_MMA(ai, bj, At, Bt) do { __builtin_amdgcn_s_setprio(1); _Pragma("unroll") for (int m = 0; m < 4; ++m) _Pragma("unroll") for (int n = 0; n < 2; ++n) _Pragma("unroll") for (int k = 0; k < 2; ++k) \
;         acc[ai][bj][m][n] = __builtin_amdgcn_mfma_f32_16x16x32_bf16(Bt[n][k], At[m][k], acc[ai][bj][m][n], 0, 0, 0); __builtin_amdgcn_s_setprio(0); } while (0)
; #define PG8_WAIT_V(n) asm volatile("s_waitcnt vmcnt(" #n ")" ::: "memory")
; #define PG8_WAIT_L(n) asm volatile("s_waitcnt lgkmcnt(" #n ")" ::: "memory")
; #define PG8_BAR __builtin_amdgcn_s_barrier()
; #define PG8_SCHED __builtin_amdgcn_sched_barrier(0)
; template <class Epi>
; DI void gemm_phase(LAS unsigned char* lds, const int tid, const Gemm g, const StaticOrder& S, const Epi& E) {
;     ...
;             PG8_LDB(B0, 1, 0); PG8_LDB(B1, 1, 1); PG8_SCHED; PG8_LDA(At, 1, 0); PG8_STAGE(PG8_SA(0, 1), a2 + hstepA, voffA);
;             PG8_WAIT_V(8); PG8_WAIT_L(0); PG8_BAR; PG8_MMA(0, 0, At, B0); PG8_MMA(0, 1, At, B1); PG8_BAR; PG8_SCHED;
;             PG8_LDA(At, 1, 1); PG8_STAGE(PG8_SB(1, 0), b3, voffB); PG8_STAGE(PG8_SB(1, 1), b3 + hstepB, voffB); PG8_STAGE(PG8_SA(1, 0), a3, voffA);
;             PG8_WAIT_V(8); PG8_WAIT_L(0); PG8_BAR; PG8_MMA(1, 0, At, B0); PG8_MMA(1, 1, At, B1); PG8_BAR; PG8_SCHED;
;         }
	s_setprio 1
	s_waitcnt lgkmcnt(0)
	v_mfma_f32_16x16x32_bf16 v[126:129], v[130:133], v[162:165], v[126:129]
	v_mfma_f32_16x16x32_bf16 v[122:125], v[138:141], v[162:165], v[122:125]
	v_mfma_f32_16x16x32_bf16 v[110:113], v[130:133], v[170:173], v[110:113]
	v_mfma_f32_16x16x32_bf16 v[106:109], v[138:141], v[170:173], v[106:109]
	v_mfma_f32_16x16x32_bf16 v[94:97], v[130:133], v[178:181], v[94:97]
	v_mfma_f32_16x16x32_bf16 v[90:93], v[138:141], v[178:181], v[90:93]
	v_mfma_f32_16x16x32_bf16 v[78:81], v[130:133], v[186:189], v[78:81]
	v_mfma_f32_16x16x32_bf16 v[74:77], v[138:141], v[186:189], v[74:77]
	v_mfma_f32_16x16x32_bf16 v[126:129], v[134:137], v[166:169], v[126:129]
	v_mfma_f32_16x16x32_bf16 v[122:125], v[142:145], v[166:169], v[122:125]
	v_mfma_f32_16x16x32_bf16 v[110:113], v[134:137], v[174:177], v[110:113]
	v_mfma_f32_16x16x32_bf16 v[106:109], v[142:145], v[174:177], v[106:109]
	v_mfma_f32_16x16x32_bf16 v[94:97], v[134:137], v[182:185], v[94:97]
	v_mfma_f32_16x16x32_bf16 v[90:93], v[142:145], v[182:185], v[90:93]
	v_mfma_f32_16x16x32_bf16 v[78:81], v[134:137], v[190:193], v[78:81]
	v_mfma_f32_16x16x32_bf16 v[74:77], v[142:145], v[190:193], v[74:77]
	s_setprio 0
	s_setprio 1
	v_mfma_f32_16x16x32_bf16 v[118:121], v[146:149], v[162:165], v[118:121]
	v_mfma_f32_16x16x32_bf16 v[114:117], v[154:157], v[162:165], v[114:117]
	v_mfma_f32_16x16x32_bf16 v[102:105], v[146:149], v[170:173], v[102:105]
	v_mfma_f32_16x16x32_bf16 v[98:101], v[154:157], v[170:173], v[98:101]
	v_mfma_f32_16x16x32_bf16 v[86:89], v[146:149], v[178:181], v[86:89]
	v_mfma_f32_16x16x32_bf16 v[82:85], v[154:157], v[178:181], v[82:85]
	v_mfma_f32_16x16x32_bf16 v[70:73], v[146:149], v[186:189], v[70:73]
	v_mfma_f32_16x16x32_bf16 v[66:69], v[154:157], v[186:189], v[66:69]
	v_mfma_f32_16x16x32_bf16 v[118:121], v[150:153], v[166:169], v[118:121]
	v_mfma_f32_16x16x32_bf16 v[114:117], v[158:161], v[166:169], v[114:117]
	v_mfma_f32_16x16x32_bf16 v[102:105], v[150:153], v[174:177], v[102:105]
	v_mfma_f32_16x16x32_bf16 v[98:101], v[158:161], v[174:177], v[98:101]
	v_mfma_f32_16x16x32_bf16 v[86:89], v[150:153], v[182:185], v[86:89]
	v_mfma_f32_16x16x32_bf16 v[82:85], v[158:161], v[182:185], v[82:85]
	v_mfma_f32_16x16x32_bf16 v[70:73], v[150:153], v[190:193], v[70:73]
	v_mfma_f32_16x16x32_bf16 v[66:69], v[158:161], v[190:193], v[66:69]
	s_setprio 0
	s_barrier
	s_add_i32 s10, s26, s30
	v_lshl_add_u64 v[194:195], v[194:195], 0, s[54:55]
	s_mov_b32 m0, s10
	ds_read_b128 v[162:165], v243 offset:49152
	ds_read_b128 v[166:169], v243 offset:50176
	ds_read_b128 v[170:173], v243 offset:51200
	ds_read_b128 v[174:177], v243 offset:52224
	ds_read_b128 v[178:181], v243 offset:53248
	ds_read_b128 v[182:185], v243 offset:54272
	ds_read_b128 v[186:189], v243 offset:55296
	ds_read_b128 v[190:193], v243 offset:56320
	global_load_lds_dwordx4 v[194:195], off
	v_lshl_add_u64 v[194:195], v[196:197], 0, s[54:55]
	s_add_i32 m0, s10, 0x2000
	s_add_i32 s10, s27, s30
	global_load_lds_dwordx4 v[194:195], off
	v_lshl_add_u64 v[194:195], v[198:199], 0, s[54:55]
	s_mov_b32 m0, s10
	s_nop 0
	global_load_lds_dwordx4 v[194:195], off
	v_lshl_add_u64 v[194:195], v[200:201], 0, s[54:55]
	s_add_i32 m0, s10, 0x2000
	s_nop 0
	global_load_lds_dwordx4 v[194:195], off
	v_lshl_add_u64 v[194:195], v[202:203], 0, s[100:101]
	s_mov_b32 m0, s25
	s_nop 0
	global_load_lds_dwordx4 v[194:195], off
	v_lshl_add_u64 v[194:195], v[204:205], 0, s[100:101]
	s_mov_b32 m0, s42
	s_nop 0
	global_load_lds_dwordx4 v[194:195], off
	s_waitcnt vmcnt(8)
	s_waitcnt lgkmcnt(0)
	s_barrier
	s_setprio 1
	s_waitcnt lgkmcnt(0)
	v_mfma_f32_16x16x32_bf16 v[62:65], v[130:133], v[162:165], v[62:65]
	v_mfma_f32_16x16x32_bf16 v[58:61], v[138:141], v[162:165], v[58:61]
	v_mfma_f32_16x16x32_bf16 v[46:49], v[130:133], v[170:173], v[46:49]
	v_mfma_f32_16x16x32_bf16 v[42:45], v[138:141], v[170:173], v[42:45]
	v_mfma_f32_16x16x32_bf16 v[30:33], v[130:133], v[178:181], v[30:33]
	v_mfma_f32_16x16x32_bf16 v[26:29], v[138:141], v[178:181], v[26:29]
	v_mfma_f32_16x16x32_bf16 v[14:17], v[130:133], v[186:189], v[14:17]
	v_mfma_f32_16x16x32_bf16 v[10:13], v[138:141], v[186:189], v[10:13]
	v_mfma_f32_16x16x32_bf16 v[62:65], v[134:137], v[166:169], v[62:65]
	v_mfma_f32_16x16x32_bf16 v[58:61], v[142:145], v[166:169], v[58:61]
	v_mfma_f32_16x16x32_bf16 v[46:49], v[134:137], v[174:177], v[46:49]
	v_mfma_f32_16x16x32_bf16 v[42:45], v[142:145], v[174:177], v[42:45]
	v_mfma_f32_16x16x32_bf16 v[30:33], v[134:137], v[182:185], v[30:33]
	v_mfma_f32_16x16x32_bf16 v[26:29], v[142:145], v[182:185], v[26:29]
	v_mfma_f32_16x16x32_bf16 v[14:17], v[134:137], v[190:193], v[14:17]
	v_mfma_f32_16x16x32_bf16 v[10:13], v[142:145], v[190:193], v[10:13]
	s_setprio 0
	s_setprio 1
	v_mfma_f32_16x16x32_bf16 v[54:57], v[146:149], v[162:165], v[54:57]
	v_mfma_f32_16x16x32_bf16 v[50:53], v[154:157], v[162:165], v[50:53]
	v_mfma_f32_16x16x32_bf16 v[38:41], v[146:149], v[170:173], v[38:41]
	v_mfma_f32_16x16x32_bf16 v[34:37], v[154:157], v[170:173], v[34:37]
	v_mfma_f32_16x16x32_bf16 v[22:25], v[146:149], v[178:181], v[22:25]
	v_mfma_f32_16x16x32_bf16 v[18:21], v[154:157], v[178:181], v[18:21]
	v_mfma_f32_16x16x32_bf16 v[6:9], v[146:149], v[186:189], v[6:9]
	v_mfma_f32_16x16x32_bf16 v[2:5], v[154:157], v[186:189], v[2:5]
	v_mfma_f32_16x16x32_bf16 v[54:57], v[150:153], v[166:169], v[54:57]
	v_mfma_f32_16x16x32_bf16 v[50:53], v[158:161], v[166:169], v[50:53]
	v_mfma_f32_16x16x32_bf16 v[38:41], v[150:153], v[174:177], v[38:41]
	v_mfma_f32_16x16x32_bf16 v[34:37], v[158:161], v[174:177], v[34:37]
	v_mfma_f32_16x16x32_bf16 v[22:25], v[150:153], v[182:185], v[22:25]
	v_mfma_f32_16x16x32_bf16 v[18:21], v[158:161], v[182:185], v[18:21]
	v_mfma_f32_16x16x32_bf16 v[6:9], v[150:153], v[190:193], v[6:9]
	v_mfma_f32_16x16x32_bf16 v[2:5], v[158:161], v[190:193], v[2:5]
	s_setprio 0
	s_barrier
	s_add_u32 s8, s8, s100
	s_addc_u32 s9, s9, 0
	s_add_u32 s8, s8, s100
	s_addc_u32 s9, s9, 0
	s_add_u32 s12, s12, 0x100
	s_addc_u32 s13, s13, 0
	s_cmp_ge_u32 s82, s96
	s_mov_b32 s10, s82
	s_cbranch_scc0 .LBB0_453
	s_and_b64 vcc, exec, s[56:57]
	s_cbranch_vccz .LBB0_456
	s_barrier

; DI unsigned cvtpk(float lo, float hi) { f32x2_t v = {lo, hi}; bf16x2_t b = __builtin_convertvector(v, bf16x2_t); return __builtin_bit_cast(unsigned, b); }
; DI float fexp2(float x) { return __builtin_amdgcn_exp2f(x); }
; DI float frcp(float x) { return __builtin_amdgcn_rcpf(x); }
;     DI void operator()(const f32x4 (&acc)[2][2][4][2], const Unit& u, int wr, int wc, int fr, int fq) const {
;         const int row0 = u.pm * BM + wr * 64 + fr, col = u.pn * 128 + wc * 32 + 8 * fq;
;         float rs8[8]; row_rstd8(rss, row0, fr + 16 * fq, fq, rs8);
; #pragma unroll
;         for (int ai = 0; ai < 2; ++ai)
; #pragma unroll
;             for (int m = 0; m < 4; ++m) {
;                 const int row = row0 + ai * HALF + m * 16;
;                 const float rstd = rs8[ai * 4 + m];
;                 float hv[8];
; #pragma unroll
;                 for (int n = 0; n < 2; ++n)
; #pragma unroll
;                     for (int j = 0; j < 4; j += 2) {
;                         const float g0 = acc[ai][0][m][n][j] * rstd, u0 = acc[ai][1][m][n][j] * rstd, g1 = acc[ai][0][m][n][j + 1] * rstd, u1 = acc[ai][1][m][n][j + 1] * rstd;
;                         const float d0 = 1.0f + fexp2(fminf(-g0 * LOG2E, 60.0f)), d1 = 1.0f + fexp2(fminf(-g1 * LOG2E, 60.0f));
;                         const float rp = frcp(d0 * d1);
;                         hv[4 * n + j] = g0 * (d1 * rp) * u0; hv[4 * n + j + 1] = g1 * (d0 * rp) * u1;
;                     }
;                 u32x4 w; w.x = cvtpk(hv[0], hv[1]); w.y = cvtpk(hv[2], hv[3]); w.z = cvtpk(hv[4], hv[5]); w.w = cvtpk(hv[6], hv[7]);
;                 *(u32x4*)(H + (size_t)row * FF + col) = w;
.Lgu_noR:
	v_lshl_add_u32 v156, s49, 8, v145
	v_lshl_or_b32 v148, s48, 7, v153
	v_lshlrev_b32_e32 v149, 5, v145
	v_add_u32_e32 v149, 0x20000, v149
	ds_read_b128 v[160:163], v149
	ds_read_b128 v[164:167], v149 offset:16
	ds_read_b128 v[168:171], v149 offset:1024
	ds_read_b128 v[172:175], v149 offset:1040
	v_lshrrev_b32_e32 v148, 5, v153
	v_lshl_add_u32 v148, s48, 2, v148
	v_lshlrev_b32_e32 v148, 10, v148
	v_and_b32_e32 v150, 7, v143
	v_lshl_add_u32 v148, v150, 7, v148
	v_lshrrev_b32_e32 v150, 3, v143
	v_lshl_add_u32 v148, v150, 6, v148
	v_bfe_u32 v150, v153, 3, 2
	v_lshl_add_u32 v148, v150, 4, v148
	v_lshrrev_b32_e32 v150, 4, v156
	v_mul_u32_u24_e32 v150, 0x16000, v150
	v_add_u32_e32 v150, v150, v148
	v_mov_b32_e32 v140, v150
	v_add_u32_e32 v141, 0x16000, v150
	v_add_u32_e32 v142, 0x2c000, v150
	v_add_u32_e32 v144, 0x42000, v150
	v_add_u32_e32 v146, 0xb0000, v150
	v_add_u32_e32 v152, 0xc6000, v150
	v_add_u32_e32 v154, 0xdc000, v150
	v_add_u32_e32 v158, 0xf2000, v150
	s_waitcnt lgkmcnt(0)
	v_mul_f32_e32 v176, 0xbfb8aa3b, v160
	v_mul_f32_e32 v178, 0xbfb8aa3b, v161
	v_mul_f32_e32 v180, 0xbfb8aa3b, v162
	v_mul_f32_e32 v182, 0xbfb8aa3b, v163
	v_mul_f32_e32 v184, 0xbfb8aa3b, v164
	v_mul_f32_e32 v186, 0xbfb8aa3b, v165
	v_mul_f32_e32 v188, 0xbfb8aa3b, v166
	v_mul_f32_e32 v190, 0xbfb8aa3b, v167
	v_mov_b32_e32 v208, v168
	v_mov_b32_e32 v210, v169
	v_mov_b32_e32 v212, v170
	v_mov_b32_e32 v214, v171
	v_mov_b32_e32 v216, v172
	v_mov_b32_e32 v218, v173
	v_mov_b32_e32 v220, v174
	v_mov_b32_e32 v222, v175
	v_pk_mul_f32 v[192:193], v[126:127], v[176:177] op_sel_hi:[1,0]
	v_pk_mul_f32 v[194:195], v[128:129], v[176:177] op_sel_hi:[1,0]
	v_pk_mul_f32 v[196:197], v[118:119], v[176:177] op_sel_hi:[1,0]
	v_pk_mul_f32 v[198:199], v[120:121], v[176:177] op_sel_hi:[1,0]
	v_exp_f32_e32 v192, v192
	v_exp_f32_e32 v193, v193
	v_exp_f32_e32 v194, v194
	v_exp_f32_e32 v195, v195
	v_exp_f32_e32 v196, v196
	v_exp_f32_e32 v197, v197
	v_exp_f32_e32 v198, v198
	v_exp_f32_e32 v199, v199
	v_pk_mul_f32 v[126:127], v[126:127], v[122:123]
	v_pk_mul_f32 v[128:129], v[128:129], v[124:125]
	v_pk_mul_f32 v[118:119], v[118:119], v[114:115]
	v_pk_mul_f32 v[120:121], v[120:121], v[116:117]
	v_pk_fma_f32 v[192:193], v[192:193], v[208:209], v[208:209] op_sel_hi:[1,0,0]
	v_pk_fma_f32 v[194:195], v[194:195], v[208:209], v[208:209] op_sel_hi:[1,0,0]
	v_pk_fma_f32 v[196:197], v[196:197], v[208:209], v[208:209] op_sel_hi:[1,0,0]
	v_pk_fma_f32 v[198:199], v[198:199], v[208:209], v[208:209] op_sel_hi:[1,0,0]
	v_rcp_f32_e32 v192, v192
	v_rcp_f32_e32 v193, v193
	v_rcp_f32_e32 v194, v194
	v_rcp_f32_e32 v195, v195
	v_rcp_f32_e32 v196, v196
	v_rcp_f32_e32 v197, v197
	v_rcp_f32_e32 v198, v198
	v_rcp_f32_e32 v199, v199
	s_nop 0
	v_pk_mul_f32 v[126:127], v[126:127], v[192:193]
	v_pk_mul_f32 v[128:129], v[128:129], v[194:195]
	v_pk_mul_f32 v[118:119], v[118:119], v[196:197]
	v_pk_mul_f32 v[120:121], v[120:121], v[198:199]
	v_cvt_pk_bf16_f32 v122, v126, v127
	v_cvt_pk_bf16_f32 v123, v128, v129
	v_cvt_pk_bf16_f32 v124, v118, v119
	v_cvt_pk_bf16_f32 v125, v120, v121
	global_store_dwordx4 v140, v[122:125], s[74:75]
	v_pk_mul_f32 v[192:193], v[110:111], v[178:179] op_sel_hi:[1,0]
	v_pk_mul_f32 v[194:195], v[112:113], v[178:179] op_sel_hi:[1,0]
	v_pk_mul_f32 v[196:197], v[102:103], v[178:179] op_sel_hi:[1,0]
	v_pk_mul_f32 v[198:199], v[104:105], v[178:179] op_sel_hi:[1,0]
	v_exp_f32_e32 v192, v192
	v_exp_f32_e32 v193, v193
	v_exp_f32_e32 v194, v194
	v_exp_f32_e32 v195, v195
	v_exp_f32_e32 v196, v196
	v_exp_f32_e32 v197, v197
	v_exp_f32_e32 v198, v198
	v_exp_f32_e32 v199, v199
	v_pk_mul_f32 v[110:111], v[110:111], v[106:107]
	v_pk_mul_f32 v[112:113], v[112:113], v[108:109]
	v_pk_mul_f32 v[102:103], v[102:103], v[98:99]
	v_pk_mul_f32 v[104:105], v[104:105], v[100:101]
	v_pk_fma_f32 v[192:193], v[192:193], v[210:211], v[210:211] op_sel_hi:[1,0,0]
	v_pk_fma_f32 v[194:195], v[194:195], v[210:211], v[210:211] op_sel_hi:[1,0,0]
	v_pk_fma_f32 v[196:197], v[196:197], v[210:211], v[210:211] op_sel_hi:[1,0,0]
	v_pk_fma_f32 v[198:199], v[198:199], v[210:211], v[210:211] op_sel_hi:[1,0,0]
	v_rcp_f32_e32 v192, v192
	v_rcp_f32_e32 v193, v193
	v_rcp_f32_e32 v194, v194
	v_rcp_f32_e32 v195, v195
	v_rcp_f32_e32 v196, v196
	v_rcp_f32_e32 v197, v197
	v_rcp_f32_e32 v198, v198
	v_rcp_f32_e32 v199, v199
	s_nop 0
	v_pk_mul_f32 v[110:111], v[110:111], v[192:193]
	v_pk_mul_f32 v[112:113], v[112:113], v[194:195]
	v_pk_mul_f32 v[102:103], v[102:103], v[196:197]
	v_pk_mul_f32 v[104:105], v[104:105], v[198:199]
	v_cvt_pk_bf16_f32 v106, v110, v111
	v_cvt_pk_bf16_f32 v107, v112, v113
	v_cvt_pk_bf16_f32 v108, v102, v103
	v_cvt_pk_bf16_f32 v109, v104, v105
	global_store_dwordx4 v141, v[106:109], s[74:75]
	v_pk_mul_f32 v[192:193], v[94:95], v[180:181] op_sel_hi:[1,0]
	v_pk_mul_f32 v[194:195], v[96:97], v[180:181] op_sel_hi:[1,0]
	v_pk_mul_f32 v[196:197], v[86:87], v[180:181] op_sel_hi:[1,0]
	v_pk_mul_f32 v[198:199], v[88:89], v[180:181] op_sel_hi:[1,0]
	v_exp_f32_e32 v192, v192
	v_exp_f32_e32 v193, v193
	v_exp_f32_e32 v194, v194
	v_exp_f32_e32 v195, v195
	v_exp_f32_e32 v196, v196
	v_exp_f32_e32 v197, v197
	v_exp_f32_e32 v198, v198
	v_exp_f32_e32 v199, v199
	v_pk_mul_f32 v[94:95], v[94:95], v[90:91]
	v_pk_mul_f32 v[96:97], v[96:97], v[92:93]
	v_pk_mul_f32 v[86:87], v[86:87], v[82:83]
	v_pk_mul_f32 v[88:89], v[88:89], v[84:85]
	v_pk_fma_f32 v[192:193], v[192:193], v[212:213], v[212:213] op_sel_hi:[1,0,0]
	v_pk_fma_f32 v[194:195], v[194:195], v[212:213], v[212:213] op_sel_hi:[1,0,0]
	v_pk_fma_f32 v[196:197], v[196:197], v[212:213], v[212:213] op_sel_hi:[1,0,0]
	v_pk_fma_f32 v[198:199], v[198:199], v[212:213], v[212:213] op_sel_hi:[1,0,0]
; DI unsigned cvtpk(float lo, float hi) { f32x2_t v = {lo, hi}; bf16x2_t b = __builtin_convertvector(v, bf16x2_t); return __builtin_bit_cast(unsigned, b); }
; DI float fexp2(float x) { return __builtin_amdgcn_exp2f(x); }
; DI float frcp(float x) { return __builtin_amdgcn_rcpf(x); }
;     DI void operator()(const f32x4 (&acc)[2][2][4][2], const Unit& u, int wr, int wc, int fr, int fq) const {
;     ...
;                 for (int n = 0; n < 2; ++n)
; #pragma unroll
;                     for (int j = 0; j < 4; j += 2) {
;                         const float g0 = acc[ai][0][m][n][j] * rstd, u0 = acc[ai][1][m][n][j] * rstd, g1 = acc[ai][0][m][n][j + 1] * rstd, u1 = acc[ai][1][m][n][j + 1] * rstd;
;                         const float d0 = 1.0f + fexp2(fminf(-g0 * LOG2E, 60.0f)), d1 = 1.0f + fexp2(fminf(-g1 * LOG2E, 60.0f));
;                         const float rp = frcp(d0 * d1);
;                         hv[4 * n + j] = g0 * (d1 * rp) * u0; hv[4 * n + j + 1] = g1 * (d0 * rp) * u1;
;                     }
;                 u32x4 w; w.x = cvtpk(hv[0], hv[1]); w.y = cvtpk(hv[2], hv[3]); w.z = cvtpk(hv[4], hv[5]); w.w = cvtpk(hv[6], hv[7]);
;                 *(u32x4*)(H + (size_t)row * FF + col) = w;
	v_rcp_f32_e32 v192, v192
	v_rcp_f32_e32 v193, v193
	v_rcp_f32_e32 v194, v194
	v_rcp_f32_e32 v195, v195
	v_rcp_f32_e32 v196, v196
	v_rcp_f32_e32 v197, v197
	v_rcp_f32_e32 v198, v198
	v_rcp_f32_e32 v199, v199
	s_nop 0
	v_pk_mul_f32 v[94:95], v[94:95], v[192:193]
	v_pk_mul_f32 v[96:97], v[96:97], v[194:195]
	v_pk_mul_f32 v[86:87], v[86:87], v[196:197]
	v_pk_mul_f32 v[88:89], v[88:89], v[198:199]
	v_cvt_pk_bf16_f32 v90, v94, v95
	v_cvt_pk_bf16_f32 v91, v96, v97
	v_cvt_pk_bf16_f32 v92, v86, v87
	v_cvt_pk_bf16_f32 v93, v88, v89
	global_store_dwordx4 v142, v[90:93], s[74:75]
	v_pk_mul_f32 v[192:193], v[78:79], v[182:183] op_sel_hi:[1,0]
	v_pk_mul_f32 v[194:195], v[80:81], v[182:183] op_sel_hi:[1,0]
	v_pk_mul_f32 v[196:197], v[70:71], v[182:183] op_sel_hi:[1,0]
	v_pk_mul_f32 v[198:199], v[72:73], v[182:183] op_sel_hi:[1,0]
	v_exp_f32_e32 v192, v192
	v_exp_f32_e32 v193, v193
	v_exp_f32_e32 v194, v194
	v_exp_f32_e32 v195, v195
	v_exp_f32_e32 v196, v196
	v_exp_f32_e32 v197, v197
	v_exp_f32_e32 v198, v198
	v_exp_f32_e32 v199, v199
	v_pk_mul_f32 v[78:79], v[78:79], v[74:75]
	v_pk_mul_f32 v[80:81], v[80:81], v[76:77]
	v_pk_mul_f32 v[70:71], v[70:71], v[66:67]
	v_pk_mul_f32 v[72:73], v[72:73], v[68:69]
	v_pk_fma_f32 v[192:193], v[192:193], v[214:215], v[214:215] op_sel_hi:[1,0,0]
	v_pk_fma_f32 v[194:195], v[194:195], v[214:215], v[214:215] op_sel_hi:[1,0,0]
	v_pk_fma_f32 v[196:197], v[196:197], v[214:215], v[214:215] op_sel_hi:[1,0,0]
	v_pk_fma_f32 v[198:199], v[198:199], v[214:215], v[214:215] op_sel_hi:[1,0,0]
	v_rcp_f32_e32 v192, v192
	v_rcp_f32_e32 v193, v193
	v_rcp_f32_e32 v194, v194
	v_rcp_f32_e32 v195, v195
	v_rcp_f32_e32 v196, v196
	v_rcp_f32_e32 v197, v197
	v_rcp_f32_e32 v198, v198
	v_rcp_f32_e32 v199, v199
	s_nop 0
	v_pk_mul_f32 v[78:79], v[78:79], v[192:193]
	v_pk_mul_f32 v[80:81], v[80:81], v[194:195]
	v_pk_mul_f32 v[70:71], v[70:71], v[196:197]
	v_pk_mul_f32 v[72:73], v[72:73], v[198:199]
	v_cvt_pk_bf16_f32 v74, v78, v79
	v_cvt_pk_bf16_f32 v75, v80, v81
	v_cvt_pk_bf16_f32 v76, v70, v71
	v_cvt_pk_bf16_f32 v77, v72, v73
	global_store_dwordx4 v144, v[74:77], s[74:75]
	v_pk_mul_f32 v[192:193], v[62:63], v[184:185] op_sel_hi:[1,0]
	v_pk_mul_f32 v[194:195], v[64:65], v[184:185] op_sel_hi:[1,0]
	v_pk_mul_f32 v[196:197], v[54:55], v[184:185] op_sel_hi:[1,0]
	v_pk_mul_f32 v[198:199], v[56:57], v[184:185] op_sel_hi:[1,0]
	v_exp_f32_e32 v192, v192
	v_exp_f32_e32 v193, v193
	v_exp_f32_e32 v194, v194
	v_exp_f32_e32 v195, v195
	v_exp_f32_e32 v196, v196
	v_exp_f32_e32 v197, v197
	v_exp_f32_e32 v198, v198
	v_exp_f32_e32 v199, v199
	v_pk_mul_f32 v[62:63], v[62:63], v[58:59]
	v_pk_mul_f32 v[64:65], v[64:65], v[60:61]
	v_pk_mul_f32 v[54:55], v[54:55], v[50:51]
	v_pk_mul_f32 v[56:57], v[56:57], v[52:53]
	v_pk_fma_f32 v[192:193], v[192:193], v[216:217], v[216:217] op_sel_hi:[1,0,0]
	v_pk_fma_f32 v[194:195], v[194:195], v[216:217], v[216:217] op_sel_hi:[1,0,0]
	v_pk_fma_f32 v[196:197], v[196:197], v[216:217], v[216:217] op_sel_hi:[1,0,0]
	v_pk_fma_f32 v[198:199], v[198:199], v[216:217], v[216:217] op_sel_hi:[1,0,0]
	v_rcp_f32_e32 v192, v192
	v_rcp_f32_e32 v193, v193
	v_rcp_f32_e32 v194, v194
	v_rcp_f32_e32 v195, v195
	v_rcp_f32_e32 v196, v196
	v_rcp_f32_e32 v197, v197
	v_rcp_f32_e32 v198, v198
	v_rcp_f32_e32 v199, v199
	s_nop 0
	v_pk_mul_f32 v[62:63], v[62:63], v[192:193]
	v_pk_mul_f32 v[64:65], v[64:65], v[194:195]
	v_pk_mul_f32 v[54:55], v[54:55], v[196:197]
	v_pk_mul_f32 v[56:57], v[56:57], v[198:199]
	v_cvt_pk_bf16_f32 v58, v62, v63
	v_cvt_pk_bf16_f32 v59, v64, v65
	v_cvt_pk_bf16_f32 v60, v54, v55
	v_cvt_pk_bf16_f32 v61, v56, v57
	global_store_dwordx4 v146, v[58:61], s[74:75]
	v_pk_mul_f32 v[192:193], v[46:47], v[186:187] op_sel_hi:[1,0]
	v_pk_mul_f32 v[194:195], v[48:49], v[186:187] op_sel_hi:[1,0]
	v_pk_mul_f32 v[196:197], v[38:39], v[186:187] op_sel_hi:[1,0]
	v_pk_mul_f32 v[198:199], v[40:41], v[186:187] op_sel_hi:[1,0]
	v_exp_f32_e32 v192, v192
	v_exp_f32_e32 v193, v193
	v_exp_f32_e32 v194, v194
	v_exp_f32_e32 v195, v195
	v_exp_f32_e32 v196, v196
	v_exp_f32_e32 v197, v197
	v_exp_f32_e32 v198, v198
	v_exp_f32_e32 v199, v199
	v_pk_mul_f32 v[46:47], v[46:47], v[42:43]
	v_pk_mul_f32 v[48:49], v[48:49], v[44:45]
; DI unsigned cvtpk(float lo, float hi) { f32x2_t v = {lo, hi}; bf16x2_t b = __builtin_convertvector(v, bf16x2_t); return __builtin_bit_cast(unsigned, b); }
; DI float fexp2(float x) { return __builtin_amdgcn_exp2f(x); }
; DI float frcp(float x) { return __builtin_amdgcn_rcpf(x); }
;     DI void operator()(const f32x4 (&acc)[2][2][4][2], const Unit& u, int wr, int wc, int fr, int fq) const {
;     ...
;                 for (int n = 0; n < 2; ++n)
; #pragma unroll
;                     for (int j = 0; j < 4; j += 2) {
;                         const float g0 = acc[ai][0][m][n][j] * rstd, u0 = acc[ai][1][m][n][j] * rstd, g1 = acc[ai][0][m][n][j + 1] * rstd, u1 = acc[ai][1][m][n][j + 1] * rstd;
;                         const float d0 = 1.0f + fexp2(fminf(-g0 * LOG2E, 60.0f)), d1 = 1.0f + fexp2(fminf(-g1 * LOG2E, 60.0f));
;                         const float rp = frcp(d0 * d1);
;                         hv[4 * n + j] = g0 * (d1 * rp) * u0; hv[4 * n + j + 1] = g1 * (d0 * rp) * u1;
;                     }
;                 u32x4 w; w.x = cvtpk(hv[0], hv[1]); w.y = cvtpk(hv[2], hv[3]); w.z = cvtpk(hv[4], hv[5]); w.w = cvtpk(hv[6], hv[7]);
;                 *(u32x4*)(H + (size_t)row * FF + col) = w;
	v_pk_mul_f32 v[38:39], v[38:39], v[34:35]
	v_pk_mul_f32 v[40:41], v[40:41], v[36:37]
	v_pk_fma_f32 v[192:193], v[192:193], v[218:219], v[218:219] op_sel_hi:[1,0,0]
	v_pk_fma_f32 v[194:195], v[194:195], v[218:219], v[218:219] op_sel_hi:[1,0,0]
	v_pk_fma_f32 v[196:197], v[196:197], v[218:219], v[218:219] op_sel_hi:[1,0,0]
	v_pk_fma_f32 v[198:199], v[198:199], v[218:219], v[218:219] op_sel_hi:[1,0,0]
	v_rcp_f32_e32 v192, v192
	v_rcp_f32_e32 v193, v193
	v_rcp_f32_e32 v194, v194
	v_rcp_f32_e32 v195, v195
	v_rcp_f32_e32 v196, v196
	v_rcp_f32_e32 v197, v197
	v_rcp_f32_e32 v198, v198
	v_rcp_f32_e32 v199, v199
	s_nop 0
	v_pk_mul_f32 v[46:47], v[46:47], v[192:193]
	v_pk_mul_f32 v[48:49], v[48:49], v[194:195]
	v_pk_mul_f32 v[38:39], v[38:39], v[196:197]
	v_pk_mul_f32 v[40:41], v[40:41], v[198:199]
	v_cvt_pk_bf16_f32 v42, v46, v47
	v_cvt_pk_bf16_f32 v43, v48, v49
	v_cvt_pk_bf16_f32 v44, v38, v39
	v_cvt_pk_bf16_f32 v45, v40, v41
	global_store_dwordx4 v152, v[42:45], s[74:75]
	v_pk_mul_f32 v[192:193], v[30:31], v[188:189] op_sel_hi:[1,0]
	v_pk_mul_f32 v[194:195], v[32:33], v[188:189] op_sel_hi:[1,0]
	v_pk_mul_f32 v[196:197], v[22:23], v[188:189] op_sel_hi:[1,0]
	v_pk_mul_f32 v[198:199], v[24:25], v[188:189] op_sel_hi:[1,0]
	v_exp_f32_e32 v192, v192
	v_exp_f32_e32 v193, v193
	v_exp_f32_e32 v194, v194
	v_exp_f32_e32 v195, v195
	v_exp_f32_e32 v196, v196
	v_exp_f32_e32 v197, v197
	v_exp_f32_e32 v198, v198
	v_exp_f32_e32 v199, v199
	v_pk_mul_f32 v[30:31], v[30:31], v[26:27]
	v_pk_mul_f32 v[32:33], v[32:33], v[28:29]
	v_pk_mul_f32 v[22:23], v[22:23], v[18:19]
	v_pk_mul_f32 v[24:25], v[24:25], v[20:21]
	v_pk_fma_f32 v[192:193], v[192:193], v[220:221], v[220:221] op_sel_hi:[1,0,0]
	v_pk_fma_f32 v[194:195], v[194:195], v[220:221], v[220:221] op_sel_hi:[1,0,0]
	v_pk_fma_f32 v[196:197], v[196:197], v[220:221], v[220:221] op_sel_hi:[1,0,0]
	v_pk_fma_f32 v[198:199], v[198:199], v[220:221], v[220:221] op_sel_hi:[1,0,0]
	v_rcp_f32_e32 v192, v192
	v_rcp_f32_e32 v193, v193
	v_rcp_f32_e32 v194, v194
	v_rcp_f32_e32 v195, v195
	v_rcp_f32_e32 v196, v196
	v_rcp_f32_e32 v197, v197
	v_rcp_f32_e32 v198, v198
	v_rcp_f32_e32 v199, v199
	s_nop 0
	v_pk_mul_f32 v[30:31], v[30:31], v[192:193]
	v_pk_mul_f32 v[32:33], v[32:33], v[194:195]
	v_pk_mul_f32 v[22:23], v[22:23], v[196:197]
	v_pk_mul_f32 v[24:25], v[24:25], v[198:199]
	v_cvt_pk_bf16_f32 v26, v30, v31
	v_cvt_pk_bf16_f32 v27, v32, v33
	v_cvt_pk_bf16_f32 v28, v22, v23
	v_cvt_pk_bf16_f32 v29, v24, v25
	global_store_dwordx4 v154, v[26:29], s[74:75]
	v_pk_mul_f32 v[192:193], v[14:15], v[190:191] op_sel_hi:[1,0]
	v_pk_mul_f32 v[194:195], v[16:17], v[190:191] op_sel_hi:[1,0]
	v_pk_mul_f32 v[196:197], v[6:7], v[190:191] op_sel_hi:[1,0]
	v_pk_mul_f32 v[198:199], v[8:9], v[190:191] op_sel_hi:[1,0]
	v_exp_f32_e32 v192, v192
	v_exp_f32_e32 v193, v193
	v_exp_f32_e32 v194, v194
	v_exp_f32_e32 v195, v195
	v_exp_f32_e32 v196, v196
	v_exp_f32_e32 v197, v197
	v_exp_f32_e32 v198, v198
	v_exp_f32_e32 v199, v199
	v_pk_mul_f32 v[14:15], v[14:15], v[10:11]
	v_pk_mul_f32 v[16:17], v[16:17], v[12:13]
	v_pk_mul_f32 v[6:7], v[6:7], v[2:3]
	v_pk_mul_f32 v[8:9], v[8:9], v[4:5]
	v_pk_fma_f32 v[192:193], v[192:193], v[222:223], v[222:223] op_sel_hi:[1,0,0]
	v_pk_fma_f32 v[194:195], v[194:195], v[222:223], v[222:223] op_sel_hi:[1,0,0]
	v_pk_fma_f32 v[196:197], v[196:197], v[222:223], v[222:223] op_sel_hi:[1,0,0]
	v_pk_fma_f32 v[198:199], v[198:199], v[222:223], v[222:223] op_sel_hi:[1,0,0]
	v_rcp_f32_e32 v192, v192
	v_rcp_f32_e32 v193, v193
	v_rcp_f32_e32 v194, v194
	v_rcp_f32_e32 v195, v195
	v_rcp_f32_e32 v196, v196
	v_rcp_f32_e32 v197, v197
	v_rcp_f32_e32 v198, v198
	v_rcp_f32_e32 v199, v199
	s_nop 0
	v_pk_mul_f32 v[14:15], v[14:15], v[192:193]
	v_pk_mul_f32 v[16:17], v[16:17], v[194:195]
	v_pk_mul_f32 v[6:7], v[6:7], v[196:197]
	v_pk_mul_f32 v[8:9], v[8:9], v[198:199]
	v_cvt_pk_bf16_f32 v10, v14, v15
	v_cvt_pk_bf16_f32 v11, v16, v17
	v_cvt_pk_bf16_f32 v12, v6, v7
	v_cvt_pk_bf16_f32 v13, v8, v9
	global_store_dwordx4 v158, v[10:13], s[74:75]
	s_andn2_b64 vcc, exec, s[4:5]
	s_mov_b64 s[6:7], -1
	s_cbranch_vccnz .LBB0_663
	s_andn2_b64 vcc, exec, s[0:1]
	s_cbranch_vccnz .LBB0_662
	s_barrier
	s_branch .LBB0_662
